# lead-half priority raise also at the GA (gate GEMM) join, priority reset before the attention loop; on top of v78
# speedup vs baseline: 1.0021x; 1.0021x over previous
; #define PG8_BAR __builtin_amdgcn_s_barrier()
;     ...
;         if (wr == 0) PG8_BAR;
;         E.template run<QV>(acc, cur, wr, wc, fr, fq);
.LBB0_790:
	s_barrier
	s_setprio 1

; #define LAS __attribute__((address_space(3)))
; __device__ __forceinline__ void attn_phase(const Args& a, int layer, LAS unsigned char* lds, int tid, int wave, int lane) {
;     unsigned char* cb = a.ws + WS_CR;
;     const bf16_t* QR = (const bf16_t*)(cb + C_QR); const bf16_t* KR = (const bf16_t*)(cb + C_KR); const bf16_t* VT = (const bf16_t*)(cb + C_VT); bf16_t* YS = (bf16_t*)(cb + C_YS);
;     const int half = lane >> 5, r31 = lane & 31;
;     const float sc2 = 0.08838834764831845f * LOG2E;
;     const int nunits = layer == 1 ? 1024 : 1024 + 32;
;     const int krow_s = tid >> 4, kc_s = tid & 15, vrow_s = tid >> 2, vc_s = tid & 3;
;     const int G_ = gridDim.x, nr = (1024 + G_ - 1) / G_;
;     for (int it = 0; ; ++it) {
;         int u;
;         if (it < nr) { u = blockIdx.x + it * G_; if (u >= 1024) continue; }
;         else { u = 1024 + (G_ - 1 - (int)blockIdx.x) + (it - nr) * G_; if (u >= nunits) break; }
;         int b, kvh, qb; bool isc;
;         if (u < 1024) { isc = false; b = u >> 8; kvh = (u >> 7) & 1; qb = u & 127; } else { const int uc = u - 1024; isc = true; b = uc >> 3; kvh = (uc >> 2) & 1; qb = uc & 3; }
;         const int th = wave & 1, g = wave >> 1, hq = kvh * 4 + g, t0 = qb * 64, tq0 = t0 + th * 32;
;         const int qrow0 = isc ? b * CTXL : MC + b * SEQ;
;         const int klo = isc ? 0 : (t0 >= 128 ? -4 : -(t0 >> 5)), khi = isc ? -1 : ((SEQ - t0) / 32 - 1 < 5 ? (SEQ - t0) / 32 - 1 : 5);
;         const int nloc = khi - klo + 1, nt = nloc + 8;
.LBB0_884:
	s_add_u32 s42, s50, 0x4de00000
	s_addc_u32 s43, s51, 0
	s_and_b64 s[2:3], s[84:85], exec
	s_movk_i32 s1, 0x420
	s_cselect_b32 s1, s1, 0x400
	s_abs_i32 s3, s60
	v_cvt_f32_u32_e32 v3, s3
	s_sub_i32 s8, 0, s3
	s_add_i32 s2, s60, 0x3ff
	s_abs_i32 s7, s2
	v_rcp_iflag_f32_e32 v3, v3
	s_xor_b32 s5, s2, s60
	s_ashr_i32 s5, s5, 31
	v_ashrrev_i32_e32 v2, 4, v131
	v_mul_f32_e32 v3, 0x4f7ffffe, v3
	v_cvt_u32_f32_e32 v3, v3
	v_readlane_b32 s12, v254, 42
	v_readlane_b32 s13, v254, 43
	v_lshlrev_b32_e32 v8, 4, v152
	v_readfirstlane_b32 s9, v3
	s_mul_i32 s8, s8, s9
	s_mul_hi_u32 s8, s9, s8
	s_add_i32 s9, s9, s8
	s_mul_hi_u32 s8, s7, s9
	s_mul_i32 s9, s8, s3
	s_sub_i32 s7, s7, s9
	s_add_i32 s9, s8, 1
	s_sub_i32 s11, s7, s3
	s_cmp_ge_u32 s7, s3
	s_cselect_b32 s8, s9, s8
	v_ashrrev_i32_e32 v3, 31, v2
	s_cselect_b32 s7, s11, s7
	s_add_i32 s9, s8, 1
	v_lshlrev_b64 v[6:7], 9, v[2:3]
	s_cmp_ge_u32 s7, s3
	v_lshl_add_u64 v[6:7], s[50:51], 0, v[6:7]
	v_mov_b32_e32 v9, v175
	s_cselect_b32 s3, s9, s8
	s_lshl_b32 s9, s12, 3
	v_lshl_add_u64 v[6:7], v[6:7], 0, v[8:9]
	s_mov_b64 s[12:13], 0x52000000
	v_and_b32_e32 v166, 48, v135
	v_mov_b32_e32 v167, v175
	v_lshl_add_u64 v[164:165], v[6:7], 0, s[12:13]
	v_lshl_add_u64 v[6:7], s[50:51], 0, v[166:167]
	s_mov_b64 s[12:13], 0x53080000
	s_xor_b32 s3, s3, s5
	v_lshl_add_u64 v[168:169], v[6:7], 0, s[12:13]
	s_movk_i32 s12, 0x110
	v_lshrrev_b32_e32 v5, 5, v171
	v_ashrrev_i32_e32 v162, 2, v131
	s_sub_i32 s3, s3, s5
	s_bfe_u32 s5, s20, 0x10006
	v_mul_lo_u32 v2, v2, s12
	s_movk_i32 s11, 0x48
	v_and_b32_e32 v177, 31, v131
	s_lshl_b32 s8, s5, 5
	v_lshlrev_b32_e32 v4, 3, v5
	v_cmp_gt_u32_e32 vcc, 32, v171
	v_add_u32_e32 v2, 0, v2
	v_mul_lo_u32 v3, v162, s11
	v_lshlrev_b32_e32 v170, 2, v5
	s_sub_i32 s11, s60, s96
	s_mov_b32 s2, 0
	s_ashr_i32 s7, s20, 7
	v_cndmask_b32_e64 v178, 0, 1.0, vcc
	v_ashrrev_i32_e32 v163, 31, v162
	v_add_u32_e32 v167, 0, v3
	v_add_u32_e32 v179, 0, v4
	v_lshlrev_b32_e32 v186, 4, v5
	v_mul_u32_u24_e32 v187, 0x48, v177
	v_mad_u32_u24 v188, v177, s12, 0
	v_or_b32_e32 v189, 1, v170
	v_or_b32_e32 v190, 2, v170
	v_or_b32_e32 v191, 3, v170
	v_or_b32_e32 v192, 8, v170
	v_or_b32_e32 v193, 9, v170
	v_or_b32_e32 v194, 10, v170
	v_or_b32_e32 v195, 11, v170
	v_or_b32_e32 v196, 16, v170
	v_or_b32_e32 v197, 17, v170
	v_or_b32_e32 v198, 18, v170
	v_or_b32_e32 v199, 19, v170
	v_or_b32_e32 v200, 24, v170
	v_or_b32_e32 v201, 25, v170
	v_or_b32_e32 v202, 26, v170
	v_or_b32_e32 v203, 27, v170
	s_addk_i32 s11, 0x3ff
	v_or_b32_e32 v204, s8, v177
	s_sub_i32 s12, 0, s5
	v_lshlrev_b32_e32 v174, 1, v4
	v_add_u32_e32 v205, v2, v8
	s_setprio 0
	v_readfirstlane_b32 s98, v0
	s_nop 3
	s_lshr_b32 s98, s98, 6
	s_cmp_ge_u32 s98, 4
	s_cbranch_scc0 .Lattn_prio_done
	s_setprio 1
